# P3 mid-K hook: all 32 gate loads issued in one batch (was 7 serialized round trips)
# speedup vs baseline: 1.0122x; 1.0077x over previous
; #define G2R(aw, bw, sh) ((float)(((aw) >> (sh)) & 0xffu) * __builtin_amdgcn_rcpf(fmaxf((float)(((bw) >> (sh)) & 0xffu), 0.5f)))
;     __device__ __forceinline__ void mid(f32x4 (&acc)[2][2][4][2], const Unit& u, int wr, int wc, int fr, int fq) const {
;         asm volatile("" : "+v"(fr), "+v"(fq));
;         const int row0 = u.pm * BM + wr * 64 + fr, col0 = u.pn * BM + wc * 32 + 8 * fq;
; #pragma unroll
;         for (int ai = 0; ai < 2; ++ai)
; #pragma unroll
;             for (int m = 0; m < 4; ++m) { const size_t r = (size_t)(row0 + ai * HALF + m * 16);
; #pragma unroll
;                 for (int bj = 0; bj < 2; ++bj) {
;                     const u32x2g a = *(const u32x2g*)(Gt + r * GC + col0 + bj * HALF), b = *(const u32x2g*)(Gt + r * GC + DM + col0 + bj * HALF);
;                     f32x4 v0 = acc[ai][bj][m][0], v1 = acc[ai][bj][m][1];
;     ...
;                     v0[0] *= G2R(a.x, b.x, 0); v0[1] *= G2R(a.x, b.x, 8); v0[2] *= G2R(a.x, b.x, 16); v0[3] *= G2R(a.x, b.x, 24);
;                     v1[0] *= G2R(a.y, b.y, 0); v1[1] *= G2R(a.y, b.y, 8); v1[2] *= G2R(a.y, b.y, 16); v1[3] *= G2R(a.y, b.y, 24);
;     ...
;                     acc[ai][bj][m][0] = v0; acc[ai][bj][m][1] = v1; }
;                 asm volatile("" ::: "memory"); }
.LBB0_306:
	s_cmp_eq_u32 s91, 2
	s_cselect_b64 s[62:63], -1, 0
	s_cmp_lg_u32 s91, 2
	s_cbranch_scc1 .LBB0_305
	v_mov_b32_e32 v128, v150
	v_mov_b32_e32 v130, v151
	s_nop 0
	v_add_u32_e32 v132, s88, v128
	v_ashrrev_i32_e32 v133, 31, v132
	v_lshl_add_u32 v130, v130, 3, s9
	v_lshlrev_b64 v[132:133], 11, v[132:133]
	v_ashrrev_i32_e32 v131, 31, v130
	v_lshl_add_u64 v[132:133], s[42:43], 0, v[132:133]
	v_lshl_add_u64 v[134:135], v[132:133], 0, v[130:131]
	global_load_dwordx2 v[184:185], v[134:135], off
	global_load_dwordx2 v[186:187], v[134:135], off offset:128
	global_load_dwordx2 v[188:189], v[134:135], off offset:1024
	global_load_dwordx2 v[190:191], v[134:135], off offset:1152
	v_lshl_add_u64 v[250:251], v[134:135], 0, s[46:47]
	global_load_dwordx2 v[192:193], v[250:251], off
	global_load_dwordx2 v[194:195], v[250:251], off offset:128
	global_load_dwordx2 v[196:197], v[250:251], off offset:1024
	global_load_dwordx2 v[198:199], v[250:251], off offset:1152
	v_lshl_add_u64 v[248:249], v[134:135], 0, s[48:49]
	global_load_dwordx2 v[200:201], v[248:249], off
	global_load_dwordx2 v[202:203], v[248:249], off offset:128
	global_load_dwordx2 v[204:205], v[248:249], off offset:1024
	global_load_dwordx2 v[206:207], v[248:249], off offset:1152
	v_lshl_add_u64 v[250:251], v[134:135], 0, s[14:15]
	global_load_dwordx2 v[208:209], v[250:251], off
	global_load_dwordx2 v[210:211], v[250:251], off offset:128
	global_load_dwordx2 v[212:213], v[250:251], off offset:1024
	global_load_dwordx2 v[214:215], v[250:251], off offset:1152
	v_lshl_add_u64 v[248:249], v[134:135], 0, s[50:51]
	global_load_dwordx2 v[216:217], v[248:249], off
	global_load_dwordx2 v[218:219], v[248:249], off offset:128
	global_load_dwordx2 v[220:221], v[248:249], off offset:1024
	global_load_dwordx2 v[222:223], v[248:249], off offset:1152
	v_lshl_add_u64 v[250:251], v[134:135], 0, s[54:55]
	global_load_dwordx2 v[224:225], v[250:251], off
	global_load_dwordx2 v[226:227], v[250:251], off offset:128
	global_load_dwordx2 v[228:229], v[250:251], off offset:1024
	global_load_dwordx2 v[230:231], v[250:251], off offset:1152
	v_lshl_add_u64 v[248:249], v[134:135], 0, s[56:57]
	global_load_dwordx2 v[232:233], v[248:249], off
	global_load_dwordx2 v[234:235], v[248:249], off offset:128
	global_load_dwordx2 v[236:237], v[248:249], off offset:1024
	global_load_dwordx2 v[238:239], v[248:249], off offset:1152
	v_lshl_add_u64 v[250:251], v[134:135], 0, s[58:59]
	global_load_dwordx2 v[240:241], v[250:251], off
	global_load_dwordx2 v[242:243], v[250:251], off offset:128
	global_load_dwordx2 v[244:245], v[250:251], off offset:1024
	global_load_dwordx2 v[246:247], v[250:251], off offset:1152
	s_waitcnt vmcnt(24)
	v_mov_b64_e32 v[130:131], v[188:189]
	v_mov_b64_e32 v[132:133], v[184:185]
	v_mov_b64_e32 v[144:145], v[190:191]
	v_mov_b64_e32 v[156:157], v[186:187]
	v_add_co_u32_e32 v138, vcc, s79, v134
	v_lshl_add_u64 v[136:137], v[134:135], 0, s[46:47]
	s_nop 0
	v_addc_co_u32_e32 v139, vcc, 0, v135, vcc
	v_mov_b64_e32 v[140:141], v[192:193]
	v_mov_b64_e32 v[142:143], v[196:197]
	s_nop 0
	v_mov_b64_e32 v[138:139], v[198:199]
	s_nop 0
	v_mov_b64_e32 v[136:137], v[194:195]
	s_waitcnt vmcnt(20)
	v_cvt_f32_ubyte2_e32 v170, v131
	v_cvt_f32_ubyte3_e32 v171, v131
	v_cvt_f32_ubyte0_e32 v172, v144
	v_cvt_f32_ubyte1_e32 v173, v144
	v_cvt_f32_ubyte2_e32 v174, v144
	v_cvt_f32_ubyte3_e32 v144, v144
	v_cvt_f32_ubyte1_e32 v175, v145
	v_max_f32_e32 v170, 0.5, v170
	v_max_f32_e32 v171, 0.5, v171
	v_max_f32_e32 v174, 0.5, v174
	v_max_f32_e32 v179, 0.5, v144
	v_cvt_f32_ubyte0_e32 v128, v130
	v_cvt_f32_ubyte1_e32 v155, v130
	v_cvt_f32_ubyte2_e32 v166, v130
	v_cvt_f32_ubyte3_e32 v167, v130
	v_cvt_f32_ubyte3_e32 v159, v132
	v_cvt_f32_ubyte2_e32 v158, v132
	v_cvt_f32_ubyte1_e32 v161, v132
	v_cvt_f32_ubyte0_e32 v160, v132
	v_cvt_f32_ubyte0_e32 v168, v131
	v_cvt_f32_ubyte1_e32 v169, v131
	v_cvt_f32_ubyte3_e32 v131, v133
	v_cvt_f32_ubyte2_e32 v130, v133
	v_cvt_f32_ubyte1_e32 v163, v133
	v_cvt_f32_ubyte0_e32 v162, v133
	v_cvt_f32_ubyte3_e32 v133, v156
	v_cvt_f32_ubyte2_e32 v132, v156
	v_cvt_f32_ubyte1_e32 v165, v156
	v_cvt_f32_ubyte0_e32 v164, v156
	v_cvt_f32_ubyte0_e32 v156, v145
	v_cvt_f32_ubyte2_e32 v178, v145
	v_cvt_f32_ubyte3_e32 v145, v145
	v_max_f32_e32 v180, 0.5, v175
	v_rcp_f32_e32 v170, v170
	v_rcp_f32_e32 v171, v171
	v_rcp_f32_e32 v174, v174
	v_rcp_f32_e32 v175, v179
	v_max_f32_e32 v156, 0.5, v156
	v_max_f32_e32 v181, 0.5, v178
	v_max_f32_e32 v182, 0.5, v145
	v_max_f32_e32 v128, 0.5, v128
	v_max_f32_e32 v155, 0.5, v155
	v_rcp_f32_e32 v178, v156
	v_rcp_f32_e32 v179, v180
	v_rcp_f32_e32 v180, v181
	v_rcp_f32_e32 v181, v182
	v_rcp_f32_e32 v144, v128
	v_rcp_f32_e32 v145, v155
	v_pk_mul_f32 v[130:131], v[170:171], v[130:131]
	v_pk_mul_f32 v[132:133], v[174:175], v[132:133]
	v_pk_mul_f32 v[118:119], v[118:119], v[130:131]
	v_pk_mul_f32 v[122:123], v[122:123], v[132:133]
	v_cvt_f32_ubyte3_e32 v131, v157
	v_cvt_f32_ubyte2_e32 v130, v157
	v_cvt_f32_ubyte1_e32 v133, v157
	v_cvt_f32_ubyte0_e32 v132, v157
	v_cvt_f32_ubyte0_e32 v128, v142
	v_pk_mul_f32 v[132:133], v[178:179], v[132:133]
	v_pk_mul_f32 v[130:131], v[180:181], v[130:131]
	v_max_f32_e32 v128, 0.5, v128
	v_pk_mul_f32 v[144:145], v[144:145], v[160:161]
	v_pk_mul_f32 v[126:127], v[126:127], v[130:131]
	v_pk_mul_f32 v[124:125], v[124:125], v[132:133]
	v_rcp_f32_e32 v130, v128
	v_cvt_f32_ubyte1_e32 v128, v142
	v_lshl_add_u64 v[132:133], v[134:135], 0, s[48:49]
	v_pk_mul_f32 v[112:113], v[112:113], v[144:145]
	v_max_f32_e32 v128, 0.5, v128
	v_mov_b64_e32 v[144:145], v[204:205]
	v_rcp_f32_e32 v131, v128
	v_cvt_f32_ubyte2_e32 v128, v142
	v_max_f32_e32 v166, 0.5, v166
	v_max_f32_e32 v167, 0.5, v167
; #define G2R(aw, bw, sh) ((float)(((aw) >> (sh)) & 0xffu) * __builtin_amdgcn_rcpf(fmaxf((float)(((bw) >> (sh)) & 0xffu), 0.5f)))
;     __device__ __forceinline__ void mid(f32x4 (&acc)[2][2][4][2], const Unit& u, int wr, int wc, int fr, int fq) const {
;     ...
;             for (int m = 0; m < 4; ++m) { const size_t r = (size_t)(row0 + ai * HALF + m * 16);
; #pragma unroll
;                 for (int bj = 0; bj < 2; ++bj) {
;                     const u32x2g a = *(const u32x2g*)(Gt + r * GC + col0 + bj * HALF), b = *(const u32x2g*)(Gt + r * GC + DM + col0 + bj * HALF);
;                     f32x4 v0 = acc[ai][bj][m][0], v1 = acc[ai][bj][m][1];
;     ...
;                     v0[0] *= G2R(a.x, b.x, 0); v0[1] *= G2R(a.x, b.x, 8); v0[2] *= G2R(a.x, b.x, 16); v0[3] *= G2R(a.x, b.x, 24);
;                     v1[0] *= G2R(a.y, b.y, 0); v1[1] *= G2R(a.y, b.y, 8); v1[2] *= G2R(a.y, b.y, 16); v1[3] *= G2R(a.y, b.y, 24);
;     ...
;                     acc[ai][bj][m][0] = v0; acc[ai][bj][m][1] = v1; }
	v_max_f32_e32 v128, 0.5, v128
	v_rcp_f32_e32 v166, v166
	v_rcp_f32_e32 v167, v167
	v_rcp_f32_e32 v156, v128
	v_cvt_f32_ubyte3_e32 v128, v142
	v_max_f32_e32 v128, 0.5, v128
	v_rcp_f32_e32 v157, v128
	v_pk_mul_f32 v[158:159], v[166:167], v[158:159]
	v_max_f32_e32 v168, 0.5, v168
	v_pk_mul_f32 v[114:115], v[114:115], v[158:159]
	v_cvt_f32_ubyte3_e32 v159, v140
	v_cvt_f32_ubyte2_e32 v158, v140
	v_pk_mul_f32 v[156:157], v[156:157], v[158:159]
	v_add_co_u32_e32 v158, vcc, s72, v134
	v_max_f32_e32 v169, 0.5, v169
	s_nop 0
	v_addc_co_u32_e32 v159, vcc, 0, v135, vcc
	v_mov_b64_e32 v[158:159], v[200:201]
	v_rcp_f32_e32 v168, v168
	v_rcp_f32_e32 v169, v169
	v_cvt_f32_ubyte0_e32 v128, v143
	v_max_f32_e32 v128, 0.5, v128
	v_pk_mul_f32 v[98:99], v[98:99], v[156:157]
	v_pk_mul_f32 v[160:161], v[168:169], v[162:163]
	v_cvt_f32_ubyte3_e32 v157, v141
	v_pk_mul_f32 v[116:117], v[116:117], v[160:161]
	v_cvt_f32_ubyte1_e32 v161, v140
	v_cvt_f32_ubyte0_e32 v160, v140
	v_pk_mul_f32 v[130:131], v[130:131], v[160:161]
	v_cvt_f32_ubyte1_e32 v161, v141
	v_pk_mul_f32 v[96:97], v[96:97], v[130:131]
	v_rcp_f32_e32 v130, v128
	v_cvt_f32_ubyte1_e32 v128, v143
	v_max_f32_e32 v128, 0.5, v128
	v_rcp_f32_e32 v131, v128
	v_cvt_f32_ubyte2_e32 v128, v143
	v_max_f32_e32 v128, 0.5, v128
	v_rcp_f32_e32 v142, v128
	v_cvt_f32_ubyte3_e32 v128, v143
	v_max_f32_e32 v128, 0.5, v128
	v_rcp_f32_e32 v143, v128
	v_cvt_f32_ubyte0_e32 v160, v141
	v_cvt_f32_ubyte0_e32 v128, v138
	v_cvt_f32_ubyte2_e32 v156, v141
	v_pk_mul_f32 v[130:131], v[130:131], v[160:161]
	v_max_f32_e32 v128, 0.5, v128
	v_pk_mul_f32 v[140:141], v[142:143], v[156:157]
	v_pk_mul_f32 v[100:101], v[100:101], v[130:131]
	v_rcp_f32_e32 v130, v128
	v_cvt_f32_ubyte1_e32 v128, v138
	v_pk_mul_f32 v[102:103], v[102:103], v[140:141]
	v_max_f32_e32 v128, 0.5, v128
	v_mov_b64_e32 v[140:141], v[206:207]
	v_rcp_f32_e32 v131, v128
	v_cvt_f32_ubyte2_e32 v128, v138
	v_max_f32_e32 v128, 0.5, v128
	v_rcp_f32_e32 v142, v128
	v_cvt_f32_ubyte3_e32 v128, v138
	v_max_f32_e32 v128, 0.5, v128
	v_rcp_f32_e32 v143, v128
	v_cvt_f32_ubyte1_e32 v161, v136
	v_cvt_f32_ubyte0_e32 v160, v136
	v_cvt_f32_ubyte0_e32 v128, v139
	v_pk_mul_f32 v[130:131], v[130:131], v[160:161]
	v_max_f32_e32 v128, 0.5, v128
	v_pk_mul_f32 v[104:105], v[104:105], v[130:131]
	v_mov_b64_e32 v[130:131], v[202:203]
	v_rcp_f32_e32 v132, v128
	v_cvt_f32_ubyte1_e32 v128, v139
	v_max_f32_e32 v128, 0.5, v128
	v_rcp_f32_e32 v133, v128
	v_cvt_f32_ubyte2_e32 v128, v139
	v_max_f32_e32 v128, 0.5, v128
	v_rcp_f32_e32 v138, v128
	v_cvt_f32_ubyte3_e32 v128, v139
	v_max_f32_e32 v128, 0.5, v128
	v_rcp_f32_e32 v139, v128
	v_cvt_f32_ubyte3_e32 v157, v136
	v_cvt_f32_ubyte2_e32 v156, v136
	v_pk_mul_f32 v[142:143], v[142:143], v[156:157]
	v_cvt_f32_ubyte1_e32 v157, v137
	v_cvt_f32_ubyte0_e32 v156, v137
	s_waitcnt vmcnt(16)
	v_cvt_f32_ubyte0_e32 v128, v144
	v_pk_mul_f32 v[106:107], v[106:107], v[142:143]
	v_cvt_f32_ubyte3_e32 v143, v137
	v_cvt_f32_ubyte2_e32 v142, v137
	v_pk_mul_f32 v[132:133], v[132:133], v[156:157]
	v_max_f32_e32 v128, 0.5, v128
	v_pk_mul_f32 v[136:137], v[138:139], v[142:143]
	v_pk_mul_f32 v[108:109], v[108:109], v[132:133]
	v_rcp_f32_e32 v132, v128
	v_cvt_f32_ubyte1_e32 v128, v144
	v_lshl_add_u64 v[138:139], v[134:135], 0, s[14:15]
	v_pk_mul_f32 v[110:111], v[110:111], v[136:137]
	v_max_f32_e32 v128, 0.5, v128
	v_mov_b64_e32 v[136:137], v[212:213]
	v_rcp_f32_e32 v133, v128
	v_cvt_f32_ubyte2_e32 v128, v144
	v_max_f32_e32 v128, 0.5, v128
	v_rcp_f32_e32 v142, v128
	v_cvt_f32_ubyte3_e32 v128, v144
	v_max_f32_e32 v128, 0.5, v128
	v_rcp_f32_e32 v143, v128
	v_cvt_f32_ubyte3_e32 v157, v158
	v_cvt_f32_ubyte2_e32 v156, v158
	v_cvt_f32_ubyte1_e32 v161, v158
	v_pk_mul_f32 v[142:143], v[142:143], v[156:157]
	v_add_co_u32_e32 v156, vcc, s78, v134
	v_cvt_f32_ubyte0_e32 v160, v158
	s_nop 0
	v_addc_co_u32_e32 v157, vcc, 0, v135, vcc
	v_mov_b64_e32 v[156:157], v[208:209]
	v_cvt_f32_ubyte0_e32 v128, v145
	v_pk_mul_f32 v[132:133], v[132:133], v[160:161]
	v_max_f32_e32 v128, 0.5, v128
	v_pk_mul_f32 v[80:81], v[80:81], v[132:133]
	v_rcp_f32_e32 v132, v128
	v_cvt_f32_ubyte1_e32 v128, v145
	v_max_f32_e32 v128, 0.5, v128
	v_rcp_f32_e32 v133, v128
	v_cvt_f32_ubyte2_e32 v128, v145
	v_max_f32_e32 v128, 0.5, v128
	v_pk_mul_f32 v[82:83], v[82:83], v[142:143]
	v_rcp_f32_e32 v142, v128
	v_cvt_f32_ubyte3_e32 v128, v145
	v_max_f32_e32 v128, 0.5, v128
	v_rcp_f32_e32 v143, v128
	v_cvt_f32_ubyte3_e32 v145, v159
	v_cvt_f32_ubyte2_e32 v144, v159
	v_cvt_f32_ubyte1_e32 v161, v159
	v_pk_mul_f32 v[142:143], v[142:143], v[144:145]
	v_cvt_f32_ubyte0_e32 v160, v159
	v_pk_mul_f32 v[86:87], v[86:87], v[142:143]
	v_cvt_f32_ubyte0_e32 v128, v140
	v_mov_b64_e32 v[142:143], v[214:215]
	v_pk_mul_f32 v[132:133], v[132:133], v[160:161]
	v_max_f32_e32 v128, 0.5, v128
	v_pk_mul_f32 v[84:85], v[84:85], v[132:133]
	v_rcp_f32_e32 v132, v128
	v_cvt_f32_ubyte1_e32 v128, v140
	v_max_f32_e32 v128, 0.5, v128
	v_rcp_f32_e32 v133, v128
	v_cvt_f32_ubyte2_e32 v128, v140
	v_max_f32_e32 v128, 0.5, v128
	v_rcp_f32_e32 v144, v128
	v_cvt_f32_ubyte3_e32 v128, v140
	v_max_f32_e32 v128, 0.5, v128
	v_rcp_f32_e32 v145, v128
	v_cvt_f32_ubyte1_e32 v161, v130
	v_cvt_f32_ubyte0_e32 v160, v130
	v_cvt_f32_ubyte0_e32 v128, v141
	v_pk_mul_f32 v[132:133], v[132:133], v[160:161]
	v_max_f32_e32 v128, 0.5, v128
	v_pk_mul_f32 v[88:89], v[88:89], v[132:133]
	v_mov_b64_e32 v[132:133], v[210:211]
	v_rcp_f32_e32 v138, v128
	v_cvt_f32_ubyte1_e32 v128, v141
	v_max_f32_e32 v128, 0.5, v128
	v_rcp_f32_e32 v139, v128
	v_cvt_f32_ubyte2_e32 v128, v141
	v_max_f32_e32 v128, 0.5, v128
	v_rcp_f32_e32 v140, v128
	v_cvt_f32_ubyte3_e32 v128, v141
	v_max_f32_e32 v128, 0.5, v128
	v_rcp_f32_e32 v141, v128
	v_cvt_f32_ubyte3_e32 v159, v130
	v_cvt_f32_ubyte2_e32 v158, v130
	v_pk_mul_f32 v[144:145], v[144:145], v[158:159]
	v_cvt_f32_ubyte1_e32 v159, v131
	v_cvt_f32_ubyte0_e32 v158, v131
	v_pk_mul_f32 v[90:91], v[90:91], v[144:145]
	v_cvt_f32_ubyte3_e32 v145, v131
	v_cvt_f32_ubyte2_e32 v144, v131
	v_pk_mul_f32 v[130:131], v[138:139], v[158:159]
	s_waitcnt vmcnt(12)
; #define G2R(aw, bw, sh) ((float)(((aw) >> (sh)) & 0xffu) * __builtin_amdgcn_rcpf(fmaxf((float)(((bw) >> (sh)) & 0xffu), 0.5f)))
;     __device__ __forceinline__ void mid(f32x4 (&acc)[2][2][4][2], const Unit& u, int wr, int wc, int fr, int fq) const {
;     ...
;             for (int m = 0; m < 4; ++m) { const size_t r = (size_t)(row0 + ai * HALF + m * 16);
; #pragma unroll
;                 for (int bj = 0; bj < 2; ++bj) {
;                     const u32x2g a = *(const u32x2g*)(Gt + r * GC + col0 + bj * HALF), b = *(const u32x2g*)(Gt + r * GC + DM + col0 + bj * HALF);
;                     f32x4 v0 = acc[ai][bj][m][0], v1 = acc[ai][bj][m][1];
;     ...
;                     v0[0] *= G2R(a.x, b.x, 0); v0[1] *= G2R(a.x, b.x, 8); v0[2] *= G2R(a.x, b.x, 16); v0[3] *= G2R(a.x, b.x, 24);
;                     v1[0] *= G2R(a.y, b.y, 0); v1[1] *= G2R(a.y, b.y, 8); v1[2] *= G2R(a.y, b.y, 16); v1[3] *= G2R(a.y, b.y, 24);
;     ...
;                     acc[ai][bj][m][0] = v0; acc[ai][bj][m][1] = v1; }
	v_cvt_f32_ubyte0_e32 v128, v136
	v_max_f32_e32 v128, 0.5, v128
	v_pk_mul_f32 v[138:139], v[140:141], v[144:145]
	v_pk_mul_f32 v[92:93], v[92:93], v[130:131]
	v_rcp_f32_e32 v130, v128
	v_cvt_f32_ubyte1_e32 v128, v136
	v_lshl_add_u64 v[144:145], v[134:135], 0, s[50:51]
	v_pk_mul_f32 v[94:95], v[94:95], v[138:139]
	v_max_f32_e32 v128, 0.5, v128
	v_mov_b64_e32 v[138:139], v[220:221]
	v_rcp_f32_e32 v131, v128
	v_cvt_f32_ubyte2_e32 v128, v136
	v_max_f32_e32 v128, 0.5, v128
	v_rcp_f32_e32 v140, v128
	v_cvt_f32_ubyte3_e32 v128, v136
	v_max_f32_e32 v128, 0.5, v128
	v_rcp_f32_e32 v141, v128
	v_cvt_f32_ubyte3_e32 v159, v156
	v_cvt_f32_ubyte2_e32 v158, v156
	v_cvt_f32_ubyte1_e32 v161, v156
	v_pk_mul_f32 v[140:141], v[140:141], v[158:159]
	v_add_co_u32_e32 v158, vcc, s80, v134
	v_cvt_f32_ubyte0_e32 v160, v156
	s_nop 0
	v_addc_co_u32_e32 v159, vcc, 0, v135, vcc
	v_mov_b64_e32 v[158:159], v[216:217]
	v_cvt_f32_ubyte0_e32 v128, v137
	v_pk_mul_f32 v[130:131], v[130:131], v[160:161]
	v_max_f32_e32 v128, 0.5, v128
	v_pk_mul_f32 v[64:65], v[64:65], v[130:131]
	v_rcp_f32_e32 v130, v128
	v_cvt_f32_ubyte1_e32 v128, v137
	v_max_f32_e32 v128, 0.5, v128
	v_rcp_f32_e32 v131, v128
	v_cvt_f32_ubyte2_e32 v128, v137
	v_max_f32_e32 v128, 0.5, v128
	v_rcp_f32_e32 v136, v128
	v_cvt_f32_ubyte3_e32 v128, v137
	v_max_f32_e32 v128, 0.5, v128
	v_rcp_f32_e32 v137, v128
	v_cvt_f32_ubyte1_e32 v161, v157
	v_cvt_f32_ubyte0_e32 v160, v157
	v_cvt_f32_ubyte0_e32 v128, v142
	v_pk_mul_f32 v[130:131], v[130:131], v[160:161]
	v_max_f32_e32 v128, 0.5, v128
	v_pk_mul_f32 v[68:69], v[68:69], v[130:131]
	v_rcp_f32_e32 v130, v128
	v_cvt_f32_ubyte1_e32 v128, v142
	v_max_f32_e32 v128, 0.5, v128
	v_pk_mul_f32 v[66:67], v[66:67], v[140:141]
	v_cvt_f32_ubyte3_e32 v141, v157
	v_cvt_f32_ubyte2_e32 v140, v157
	v_rcp_f32_e32 v131, v128
	v_cvt_f32_ubyte2_e32 v128, v142
	v_pk_mul_f32 v[136:137], v[136:137], v[140:141]
	v_max_f32_e32 v128, 0.5, v128
	v_mov_b64_e32 v[140:141], v[222:223]
	v_pk_mul_f32 v[70:71], v[70:71], v[136:137]
	v_rcp_f32_e32 v136, v128
	v_cvt_f32_ubyte3_e32 v128, v142
	v_max_f32_e32 v128, 0.5, v128
	v_rcp_f32_e32 v137, v128
	v_cvt_f32_ubyte3_e32 v157, v132
	v_cvt_f32_ubyte2_e32 v156, v132
	v_cvt_f32_ubyte0_e32 v128, v143
	v_pk_mul_f32 v[136:137], v[136:137], v[156:157]
	v_max_f32_e32 v128, 0.5, v128
	v_cvt_f32_ubyte1_e32 v161, v132
	v_cvt_f32_ubyte0_e32 v160, v132
	v_pk_mul_f32 v[74:75], v[74:75], v[136:137]
	v_rcp_f32_e32 v136, v128
	v_cvt_f32_ubyte1_e32 v128, v143
	v_pk_mul_f32 v[130:131], v[130:131], v[160:161]
	v_max_f32_e32 v128, 0.5, v128
	v_pk_mul_f32 v[72:73], v[72:73], v[130:131]
	v_mov_b64_e32 v[130:131], v[218:219]
	v_rcp_f32_e32 v137, v128
	v_cvt_f32_ubyte2_e32 v128, v143
	v_max_f32_e32 v128, 0.5, v128
	v_rcp_f32_e32 v142, v128
	v_cvt_f32_ubyte3_e32 v128, v143
	v_max_f32_e32 v128, 0.5, v128
	v_rcp_f32_e32 v143, v128
	v_cvt_f32_ubyte1_e32 v157, v133
	v_cvt_f32_ubyte0_e32 v156, v133
	v_cvt_f32_ubyte3_e32 v145, v133
	v_cvt_f32_ubyte2_e32 v144, v133
	v_pk_mul_f32 v[132:133], v[136:137], v[156:157]
	s_waitcnt vmcnt(8)
	v_cvt_f32_ubyte0_e32 v128, v138
	v_max_f32_e32 v128, 0.5, v128
	v_pk_mul_f32 v[136:137], v[142:143], v[144:145]
	v_pk_mul_f32 v[76:77], v[76:77], v[132:133]
	v_rcp_f32_e32 v132, v128
	v_cvt_f32_ubyte1_e32 v128, v138
	v_lshl_add_u64 v[144:145], v[134:135], 0, s[54:55]
	v_pk_mul_f32 v[78:79], v[78:79], v[136:137]
	v_max_f32_e32 v128, 0.5, v128
	v_mov_b64_e32 v[136:137], v[228:229]
	v_rcp_f32_e32 v133, v128
	v_cvt_f32_ubyte2_e32 v128, v138
	v_max_f32_e32 v128, 0.5, v128
	v_rcp_f32_e32 v142, v128
	v_cvt_f32_ubyte3_e32 v128, v138
	v_max_f32_e32 v128, 0.5, v128
	v_rcp_f32_e32 v143, v128
	v_cvt_f32_ubyte3_e32 v157, v158
	v_cvt_f32_ubyte2_e32 v156, v158
	v_cvt_f32_ubyte1_e32 v161, v158
	v_pk_mul_f32 v[142:143], v[142:143], v[156:157]
	v_add_co_u32_e32 v156, vcc, s81, v134
	v_cvt_f32_ubyte0_e32 v160, v158
	s_nop 0
	v_addc_co_u32_e32 v157, vcc, 0, v135, vcc
	v_mov_b64_e32 v[156:157], v[224:225]
	v_cvt_f32_ubyte0_e32 v128, v139
	v_pk_mul_f32 v[132:133], v[132:133], v[160:161]
	v_max_f32_e32 v128, 0.5, v128
	v_pk_mul_f32 v[48:49], v[48:49], v[132:133]
	v_rcp_f32_e32 v132, v128
	v_cvt_f32_ubyte1_e32 v128, v139
	v_max_f32_e32 v128, 0.5, v128
	v_rcp_f32_e32 v133, v128
	v_cvt_f32_ubyte2_e32 v128, v139
	v_max_f32_e32 v128, 0.5, v128
	v_rcp_f32_e32 v138, v128
	v_cvt_f32_ubyte3_e32 v128, v139
	v_max_f32_e32 v128, 0.5, v128
	v_rcp_f32_e32 v139, v128
	v_cvt_f32_ubyte1_e32 v161, v159
	v_cvt_f32_ubyte0_e32 v160, v159
	v_pk_mul_f32 v[132:133], v[132:133], v[160:161]
	v_pk_mul_f32 v[50:51], v[50:51], v[142:143]
	v_pk_mul_f32 v[52:53], v[52:53], v[132:133]
	v_cvt_f32_ubyte3_e32 v143, v159
	v_cvt_f32_ubyte0_e32 v128, v140
	v_max_f32_e32 v128, 0.5, v128
	v_rcp_f32_e32 v132, v128
	v_cvt_f32_ubyte1_e32 v128, v140
	v_cvt_f32_ubyte2_e32 v142, v159
	v_max_f32_e32 v128, 0.5, v128
	v_pk_mul_f32 v[138:139], v[138:139], v[142:143]
	v_rcp_f32_e32 v133, v128
	v_cvt_f32_ubyte2_e32 v128, v140
	v_mov_b64_e32 v[142:143], v[230:231]
	v_max_f32_e32 v128, 0.5, v128
	v_pk_mul_f32 v[54:55], v[54:55], v[138:139]
	v_rcp_f32_e32 v138, v128
	v_cvt_f32_ubyte3_e32 v128, v140
	v_max_f32_e32 v128, 0.5, v128
	v_rcp_f32_e32 v139, v128
	v_cvt_f32_ubyte0_e32 v128, v141
	v_max_f32_e32 v128, 0.5, v128
	v_max_f32_e32 v172, 0.5, v172
	v_cvt_f32_ubyte1_e32 v161, v130
	v_cvt_f32_ubyte0_e32 v160, v130
	v_cvt_f32_ubyte3_e32 v159, v130
	v_cvt_f32_ubyte2_e32 v158, v130
	v_pk_mul_f32 v[132:133], v[132:133], v[160:161]
	v_pk_mul_f32 v[138:139], v[138:139], v[158:159]
	v_pk_mul_f32 v[56:57], v[56:57], v[132:133]
	v_mov_b64_e32 v[132:133], v[226:227]
	v_pk_mul_f32 v[58:59], v[58:59], v[138:139]
	v_rcp_f32_e32 v138, v128
	v_cvt_f32_ubyte1_e32 v128, v141
	v_max_f32_e32 v128, 0.5, v128
	v_rcp_f32_e32 v139, v128
	v_cvt_f32_ubyte2_e32 v128, v141
	v_max_f32_e32 v128, 0.5, v128
	v_rcp_f32_e32 v140, v128
	v_cvt_f32_ubyte3_e32 v128, v141
	v_max_f32_e32 v128, 0.5, v128
	v_rcp_f32_e32 v141, v128
	v_cvt_f32_ubyte1_e32 v159, v131
	v_cvt_f32_ubyte0_e32 v158, v131
	v_cvt_f32_ubyte3_e32 v145, v131
	v_cvt_f32_ubyte2_e32 v144, v131
	s_waitcnt vmcnt(4)
; #define G2R(aw, bw, sh) ((float)(((aw) >> (sh)) & 0xffu) * __builtin_amdgcn_rcpf(fmaxf((float)(((bw) >> (sh)) & 0xffu), 0.5f)))
;     __device__ __forceinline__ void mid(f32x4 (&acc)[2][2][4][2], const Unit& u, int wr, int wc, int fr, int fq) const {
;     ...
;             for (int m = 0; m < 4; ++m) { const size_t r = (size_t)(row0 + ai * HALF + m * 16);
; #pragma unroll
;                 for (int bj = 0; bj < 2; ++bj) {
;                     const u32x2g a = *(const u32x2g*)(Gt + r * GC + col0 + bj * HALF), b = *(const u32x2g*)(Gt + r * GC + DM + col0 + bj * HALF);
;                     f32x4 v0 = acc[ai][bj][m][0], v1 = acc[ai][bj][m][1];
;     ...
;                     v0[0] *= G2R(a.x, b.x, 0); v0[1] *= G2R(a.x, b.x, 8); v0[2] *= G2R(a.x, b.x, 16); v0[3] *= G2R(a.x, b.x, 24);
;                     v1[0] *= G2R(a.y, b.y, 0); v1[1] *= G2R(a.y, b.y, 8); v1[2] *= G2R(a.y, b.y, 16); v1[3] *= G2R(a.y, b.y, 24);
;     ...
;                     acc[ai][bj][m][0] = v0; acc[ai][bj][m][1] = v1; }
	v_cvt_f32_ubyte0_e32 v128, v136
	v_pk_mul_f32 v[130:131], v[138:139], v[158:159]
	v_max_f32_e32 v128, 0.5, v128
	v_pk_mul_f32 v[60:61], v[60:61], v[130:131]
	v_rcp_f32_e32 v130, v128
	v_cvt_f32_ubyte1_e32 v128, v136
	v_max_f32_e32 v128, 0.5, v128
	v_rcp_f32_e32 v131, v128
	v_cvt_f32_ubyte2_e32 v128, v136
	v_pk_mul_f32 v[138:139], v[140:141], v[144:145]
	v_max_f32_e32 v128, 0.5, v128
	v_lshl_add_u64 v[140:141], v[134:135], 0, s[56:57]
	v_pk_mul_f32 v[62:63], v[62:63], v[138:139]
	v_mov_b64_e32 v[138:139], v[236:237]
	v_rcp_f32_e32 v144, v128
	v_cvt_f32_ubyte3_e32 v128, v136
	v_max_f32_e32 v128, 0.5, v128
	v_rcp_f32_e32 v145, v128
	v_cvt_f32_ubyte3_e32 v159, v156
	v_cvt_f32_ubyte2_e32 v158, v156
	v_cvt_f32_ubyte1_e32 v161, v156
	v_pk_mul_f32 v[144:145], v[144:145], v[158:159]
	v_add_co_u32_e32 v158, vcc, s82, v134
	v_cvt_f32_ubyte0_e32 v160, v156
	s_nop 0
	v_addc_co_u32_e32 v159, vcc, 0, v135, vcc
	v_mov_b64_e32 v[158:159], v[232:233]
	v_cvt_f32_ubyte0_e32 v128, v137
	v_pk_mul_f32 v[130:131], v[130:131], v[160:161]
	v_max_f32_e32 v128, 0.5, v128
	v_pk_mul_f32 v[32:33], v[32:33], v[130:131]
	v_rcp_f32_e32 v130, v128
	v_cvt_f32_ubyte1_e32 v128, v137
	v_max_f32_e32 v128, 0.5, v128
	v_rcp_f32_e32 v131, v128
	v_cvt_f32_ubyte2_e32 v128, v137
	v_max_f32_e32 v128, 0.5, v128
	v_rcp_f32_e32 v136, v128
	v_cvt_f32_ubyte3_e32 v128, v137
	v_max_f32_e32 v128, 0.5, v128
	v_rcp_f32_e32 v137, v128
	v_cvt_f32_ubyte1_e32 v161, v157
	v_cvt_f32_ubyte0_e32 v160, v157
	v_pk_mul_f32 v[130:131], v[130:131], v[160:161]
	v_pk_mul_f32 v[34:35], v[34:35], v[144:145]
	v_cvt_f32_ubyte0_e32 v128, v142
	v_max_f32_e32 v128, 0.5, v128
	v_pk_mul_f32 v[36:37], v[36:37], v[130:131]
	v_rcp_f32_e32 v130, v128
	v_cvt_f32_ubyte1_e32 v128, v142
	v_max_f32_e32 v128, 0.5, v128
	v_cvt_f32_ubyte3_e32 v145, v157
	v_cvt_f32_ubyte2_e32 v144, v157
	v_rcp_f32_e32 v131, v128
	v_cvt_f32_ubyte2_e32 v128, v142
	v_pk_mul_f32 v[136:137], v[136:137], v[144:145]
	v_max_f32_e32 v128, 0.5, v128
	v_pk_mul_f32 v[38:39], v[38:39], v[136:137]
	v_rcp_f32_e32 v144, v128
	v_cvt_f32_ubyte3_e32 v128, v142
	v_mov_b64_e32 v[136:137], v[238:239]
	v_max_f32_e32 v128, 0.5, v128
	v_rcp_f32_e32 v145, v128
	v_cvt_f32_ubyte1_e32 v161, v132
	v_cvt_f32_ubyte0_e32 v160, v132
	v_cvt_f32_ubyte0_e32 v128, v143
	v_pk_mul_f32 v[130:131], v[130:131], v[160:161]
	v_max_f32_e32 v128, 0.5, v128
	v_pk_mul_f32 v[40:41], v[40:41], v[130:131]
	v_mov_b64_e32 v[130:131], v[234:235]
	v_rcp_f32_e32 v140, v128
	v_cvt_f32_ubyte1_e32 v128, v143
	v_max_f32_e32 v128, 0.5, v128
	v_rcp_f32_e32 v141, v128
	v_cvt_f32_ubyte2_e32 v128, v143
	v_max_f32_e32 v128, 0.5, v128
	v_rcp_f32_e32 v142, v128
	v_cvt_f32_ubyte3_e32 v128, v143
	v_max_f32_e32 v128, 0.5, v128
	v_rcp_f32_e32 v143, v128
	v_cvt_f32_ubyte3_e32 v157, v132
	v_cvt_f32_ubyte2_e32 v156, v132
	v_pk_mul_f32 v[144:145], v[144:145], v[156:157]
	v_cvt_f32_ubyte1_e32 v157, v133
	v_pk_mul_f32 v[42:43], v[42:43], v[144:145]
	v_cvt_f32_ubyte3_e32 v145, v133
	v_cvt_f32_ubyte2_e32 v144, v133
	v_cvt_f32_ubyte0_e32 v156, v133
	v_pk_mul_f32 v[132:133], v[140:141], v[156:157]
	v_pk_mul_f32 v[140:141], v[142:143], v[144:145]
	v_pk_mul_f32 v[44:45], v[44:45], v[132:133]
	v_pk_mul_f32 v[46:47], v[46:47], v[140:141]
	s_waitcnt vmcnt(0)
; #define G2R(aw, bw, sh) ((float)(((aw) >> (sh)) & 0xffu) * __builtin_amdgcn_rcpf(fmaxf((float)(((bw) >> (sh)) & 0xffu), 0.5f)))
;     __device__ __forceinline__ void mid(f32x4 (&acc)[2][2][4][2], const Unit& u, int wr, int wc, int fr, int fq) const {
;     ...
;             for (int m = 0; m < 4; ++m) { const size_t r = (size_t)(row0 + ai * HALF + m * 16);
; #pragma unroll
;                 for (int bj = 0; bj < 2; ++bj) {
;                     const u32x2g a = *(const u32x2g*)(Gt + r * GC + col0 + bj * HALF), b = *(const u32x2g*)(Gt + r * GC + DM + col0 + bj * HALF);
;                     f32x4 v0 = acc[ai][bj][m][0], v1 = acc[ai][bj][m][1];
;     ...
;                     v0[0] *= G2R(a.x, b.x, 0); v0[1] *= G2R(a.x, b.x, 8); v0[2] *= G2R(a.x, b.x, 16); v0[3] *= G2R(a.x, b.x, 24);
;                     v1[0] *= G2R(a.y, b.y, 0); v1[1] *= G2R(a.y, b.y, 8); v1[2] *= G2R(a.y, b.y, 16); v1[3] *= G2R(a.y, b.y, 24);
;     ...
;                     acc[ai][bj][m][0] = v0; acc[ai][bj][m][1] = v1; }
	v_cvt_f32_ubyte0_e32 v128, v138
	v_lshl_add_u64 v[140:141], v[134:135], 0, s[58:59]
	v_max_f32_e32 v128, 0.5, v128
	v_mov_b64_e32 v[142:143], v[244:245]
	v_rcp_f32_e32 v132, v128
	v_cvt_f32_ubyte1_e32 v128, v138
	v_max_f32_e32 v128, 0.5, v128
	v_rcp_f32_e32 v133, v128
	v_cvt_f32_ubyte2_e32 v128, v138
	v_max_f32_e32 v128, 0.5, v128
	v_rcp_f32_e32 v144, v128
	v_cvt_f32_ubyte3_e32 v128, v138
	v_max_f32_e32 v128, 0.5, v128
	v_add_co_u32_e32 v134, vcc, s83, v134
	v_rcp_f32_e32 v145, v128
	v_cvt_f32_ubyte1_e32 v161, v158
	v_addc_co_u32_e32 v135, vcc, 0, v135, vcc
	v_cvt_f32_ubyte0_e32 v160, v158
	v_cvt_f32_ubyte0_e32 v128, v139
	v_mov_b64_e32 v[134:135], v[240:241]
	v_pk_mul_f32 v[132:133], v[132:133], v[160:161]
	v_max_f32_e32 v128, 0.5, v128
	v_pk_mul_f32 v[16:17], v[16:17], v[132:133]
	v_rcp_f32_e32 v132, v128
	v_cvt_f32_ubyte1_e32 v128, v139
	v_max_f32_e32 v128, 0.5, v128
	v_rcp_f32_e32 v133, v128
	v_cvt_f32_ubyte3_e32 v157, v158
	v_cvt_f32_ubyte2_e32 v156, v158
	v_pk_mul_f32 v[144:145], v[144:145], v[156:157]
	v_cvt_f32_ubyte1_e32 v157, v159
	v_cvt_f32_ubyte0_e32 v156, v159
	v_pk_mul_f32 v[132:133], v[132:133], v[156:157]
	v_cvt_f32_ubyte2_e32 v128, v139
	v_pk_mul_f32 v[20:21], v[20:21], v[132:133]
	v_mov_b64_e32 v[132:133], v[246:247]
	v_max_f32_e32 v128, 0.5, v128
	v_mov_b64_e32 v[140:141], v[242:243]
	v_rcp_f32_e32 v138, v128
	v_cvt_f32_ubyte3_e32 v128, v139
	v_max_f32_e32 v128, 0.5, v128
	v_rcp_f32_e32 v139, v128
	v_pk_mul_f32 v[18:19], v[18:19], v[144:145]
	v_cvt_f32_ubyte3_e32 v145, v159
	v_cvt_f32_ubyte2_e32 v144, v159
	v_cvt_f32_ubyte0_e32 v128, v136
	v_pk_mul_f32 v[138:139], v[138:139], v[144:145]
	v_max_f32_e32 v128, 0.5, v128
	v_pk_mul_f32 v[22:23], v[22:23], v[138:139]
	v_rcp_f32_e32 v138, v128
	v_cvt_f32_ubyte1_e32 v128, v136
	v_max_f32_e32 v128, 0.5, v128
	v_rcp_f32_e32 v139, v128
	v_cvt_f32_ubyte2_e32 v128, v136
	v_max_f32_e32 v128, 0.5, v128
	v_rcp_f32_e32 v144, v128
	v_cvt_f32_ubyte3_e32 v128, v136
	v_max_f32_e32 v128, 0.5, v128
	v_rcp_f32_e32 v145, v128
	v_cvt_f32_ubyte1_e32 v159, v130
	v_cvt_f32_ubyte0_e32 v158, v130
	v_cvt_f32_ubyte0_e32 v128, v137
	v_pk_mul_f32 v[138:139], v[138:139], v[158:159]
	v_max_f32_e32 v128, 0.5, v128
	v_pk_mul_f32 v[24:25], v[24:25], v[138:139]
	v_rcp_f32_e32 v138, v128
	v_cvt_f32_ubyte1_e32 v128, v137
	v_max_f32_e32 v128, 0.5, v128
	v_rcp_f32_e32 v139, v128
	v_cvt_f32_ubyte2_e32 v128, v137
	v_max_f32_e32 v128, 0.5, v128
	v_rcp_f32_e32 v136, v128
	v_cvt_f32_ubyte3_e32 v128, v137
	v_cvt_f32_ubyte3_e32 v157, v130
	v_cvt_f32_ubyte2_e32 v156, v130
	v_max_f32_e32 v128, 0.5, v128
	v_pk_mul_f32 v[144:145], v[144:145], v[156:157]
	v_rcp_f32_e32 v137, v128
	v_cvt_f32_ubyte1_e32 v157, v131
	v_cvt_f32_ubyte0_e32 v156, v131
	v_pk_mul_f32 v[26:27], v[26:27], v[144:145]
	s_waitcnt vmcnt(0)
	v_cvt_f32_ubyte0_e32 v128, v142
	v_cvt_f32_ubyte3_e32 v145, v131
	v_cvt_f32_ubyte2_e32 v144, v131
	v_pk_mul_f32 v[130:131], v[138:139], v[156:157]
	v_max_f32_e32 v128, 0.5, v128
	v_pk_mul_f32 v[28:29], v[28:29], v[130:131]
	v_rcp_f32_e32 v130, v128
	v_cvt_f32_ubyte1_e32 v128, v142
	v_max_f32_e32 v128, 0.5, v128
	v_rcp_f32_e32 v131, v128
	v_cvt_f32_ubyte2_e32 v128, v142
	v_pk_mul_f32 v[136:137], v[136:137], v[144:145]
	v_max_f32_e32 v128, 0.5, v128
	v_pk_mul_f32 v[30:31], v[30:31], v[136:137]
	v_rcp_f32_e32 v136, v128
	v_cvt_f32_ubyte3_e32 v128, v142
	v_max_f32_e32 v128, 0.5, v128
	v_rcp_f32_e32 v137, v128
	v_cvt_f32_ubyte1_e32 v145, v134
	v_cvt_f32_ubyte0_e32 v144, v134
	v_cvt_f32_ubyte0_e32 v128, v143
	v_pk_mul_f32 v[130:131], v[130:131], v[144:145]
	v_max_f32_e32 v128, 0.5, v128
	v_pk_mul_f32 v[4:5], v[4:5], v[130:131]
	v_rcp_f32_e32 v130, v128
	v_cvt_f32_ubyte1_e32 v128, v143
	v_max_f32_e32 v128, 0.5, v128
	v_cvt_f32_ubyte3_e32 v139, v134
	v_cvt_f32_ubyte2_e32 v138, v134
	v_rcp_f32_e32 v131, v128
	v_cvt_f32_ubyte2_e32 v128, v143
	v_pk_mul_f32 v[136:137], v[136:137], v[138:139]
	v_max_f32_e32 v128, 0.5, v128
	v_pk_mul_f32 v[6:7], v[6:7], v[136:137]
	v_rcp_f32_e32 v136, v128
	v_cvt_f32_ubyte3_e32 v128, v143
	v_max_f32_e32 v128, 0.5, v128
	v_rcp_f32_e32 v137, v128
	v_cvt_f32_ubyte1_e32 v143, v135
	v_cvt_f32_ubyte0_e32 v142, v135
	v_cvt_f32_ubyte0_e32 v128, v132
	v_pk_mul_f32 v[130:131], v[130:131], v[142:143]
	v_max_f32_e32 v128, 0.5, v128
	v_pk_mul_f32 v[8:9], v[8:9], v[130:131]
	v_rcp_f32_e32 v130, v128
	v_cvt_f32_ubyte1_e32 v128, v132
	v_max_f32_e32 v128, 0.5, v128
	v_cvt_f32_ubyte3_e32 v139, v135
	v_cvt_f32_ubyte2_e32 v138, v135
	v_rcp_f32_e32 v131, v128
	v_cvt_f32_ubyte2_e32 v128, v132
	v_pk_mul_f32 v[134:135], v[136:137], v[138:139]
	v_max_f32_e32 v128, 0.5, v128
	v_pk_mul_f32 v[10:11], v[10:11], v[134:135]
	v_rcp_f32_e32 v134, v128
	v_cvt_f32_ubyte3_e32 v128, v132
	v_max_f32_e32 v128, 0.5, v128
	v_rcp_f32_e32 v135, v128
	v_cvt_f32_ubyte1_e32 v139, v140
	v_cvt_f32_ubyte0_e32 v138, v140
	v_cvt_f32_ubyte0_e32 v128, v133
	v_pk_mul_f32 v[130:131], v[130:131], v[138:139]
	v_max_f32_e32 v128, 0.5, v128
	v_pk_mul_f32 v[12:13], v[12:13], v[130:131]
	v_rcp_f32_e32 v130, v128
	v_cvt_f32_ubyte1_e32 v128, v133
	v_max_f32_e32 v128, 0.5, v128
	v_rcp_f32_e32 v131, v128
	v_cvt_f32_ubyte2_e32 v128, v133
	v_max_f32_e32 v128, 0.5, v128
	v_rcp_f32_e32 v132, v128
	v_cvt_f32_ubyte3_e32 v128, v133
	v_max_f32_e32 v173, 0.5, v173
	v_max_f32_e32 v128, 0.5, v128
	v_rcp_f32_e32 v172, v172
	v_rcp_f32_e32 v173, v173
	v_rcp_f32_e32 v133, v128
	v_cvt_f32_ubyte3_e32 v137, v140
	v_cvt_f32_ubyte2_e32 v136, v140
	v_pk_mul_f32 v[134:135], v[134:135], v[136:137]
	v_cvt_f32_ubyte1_e32 v137, v141
	v_pk_mul_f32 v[14:15], v[14:15], v[134:135]
	v_cvt_f32_ubyte3_e32 v135, v141
	v_cvt_f32_ubyte2_e32 v134, v141
	v_cvt_f32_ubyte0_e32 v136, v141
	v_pk_mul_f32 v[162:163], v[172:173], v[164:165]
	v_pk_mul_f32 v[130:131], v[130:131], v[136:137]
	v_pk_mul_f32 v[132:133], v[132:133], v[134:135]
	v_pk_mul_f32 v[120:121], v[120:121], v[162:163]
	v_pk_mul_f32 v[2:3], v[2:3], v[132:133]
	v_pk_mul_f32 v[0:1], v[0:1], v[130:131]
	s_branch .LBB0_305
